# barrier: per-XCC arrival election, XCC leaders add to one cross-XCC counter that every workgroup polls directly (no returning second-level atomic, no release hop)
# speedup vs baseline: 1.0035x; 1.0035x over previous
.Lb_nowb:
	v_mov_b32_e32 v4, 1
	s_waitcnt vmcnt(0)
	global_atomic_add v1, v4, s[10:11]
.Lb_wait:
	s_mul_i32 s16, s15, s14
	s_mov_b32 s12, 0
.Lb_spin:
	global_load_dword v4, v1, s[10:11] sc1
	s_waitcnt vmcnt(0)
	v_readfirstlane_b32 s13, v4
	s_cmp_ge_u32 s13, s16
	s_cbranch_scc1 .Lb_done
	s_sleep 1
	s_add_i32 s12, s12, 1
	s_cmp_lt_u32 s12, 0x800
	s_cbranch_scc1 .Lb_spin
